# indexer loop: previous tile's score post-processing interleaved between the four dependent MFMAs of the current tile
# baseline (speedup 1.0000x reference)
.Lidx_lddone0:
.Lidx_entry0:
	s_cmp_gt_i32 s16, s13
	s_cbranch_scc1 .Lidx_exit_prev1
	s_cmp_lt_i32 s14, 0
	s_cbranch_scc1 .Lidx_nopost0
	s_cmp_gt_i32 s14, s19
	s_cbranch_scc1 .Lidx_edge0
	s_waitcnt vmcnt(7)
	v_mfma_f32_32x32x16_bf16 v[20:35], v[44:47], v[80:83], 0
	v_max_i32_e32 v177, 0, v4
	v_max_i32_e32 v176, 0, v12
	v_max_i32_e32 v179, 0, v5
	v_pk_fma_f32 v[176:177], v[134:135], v[176:177], 0 op_sel_hi:[1,1,0]
	v_max_i32_e32 v178, 0, v13
	v_max_i32_e32 v181, 0, v6
	v_max_i32_e32 v180, 0, v14
	v_pk_fma_f32 v[176:177], v[36:37], v[178:179], v[176:177]
	v_lshl_add_u32 v189, s14, 7, v175
	v_pk_fma_f32 v[176:177], v[136:137], v[180:181], v[176:177]
	s_waitcnt vmcnt(6)
	v_mfma_f32_32x32x16_bf16 v[20:35], v[48:51], v[76:79], v[20:35]
	v_max_i32_e32 v179, 0, v7
	v_max_i32_e32 v178, 0, v15
	v_pk_fma_f32 v[176:177], v[38:39], v[178:179], v[176:177]
	v_max_i32_e32 v179, 0, v8
	v_max_i32_e32 v178, 0, v16
	v_pk_fma_f32 v[176:177], v[138:139], v[178:179], v[176:177]
	v_max_i32_e32 v179, 0, v9
	v_max_i32_e32 v178, 0, v17
	v_pk_fma_f32 v[176:177], v[40:41], v[178:179], v[176:177]
	v_max_i32_e32 v179, 0, v10
	s_waitcnt vmcnt(5)
	v_mfma_f32_32x32x16_bf16 v[20:35], v[52:55], v[72:75], v[20:35]
	v_max_i32_e32 v178, 0, v18
	v_pk_fma_f32 v[176:177], v[140:141], v[178:179], v[176:177]
	v_max_i32_e32 v179, 0, v11
	v_max_i32_e32 v178, 0, v19
	v_pk_fma_f32 v[176:177], v[42:43], v[178:179], v[176:177]
	s_nop 0
	v_ashrrev_i32_e32 v182, 31, v177
	v_ashrrev_i32_e32 v183, 31, v176
	v_bitop3_b32 v186, v177, v182, s18 bitop3:0x1e
	v_bitop3_b32 v187, v176, v183, s18 bitop3:0x1e
	s_waitcnt vmcnt(4)
	v_mfma_f32_32x32x16_bf16 v[20:35], v[56:59], v[68:71], v[20:35]
	ds_write2st64_b32 v189, v186, v187 offset1:128
	v_bfe_u32 v190, v186, 22, 10
	v_bfe_u32 v191, v186, 21, 1
	v_lshl_add_u32 v190, v190, 2, v165
	v_mad_u32_u24 v191, v191, s11, 1
	ds_add_u32 v190, v191
	v_bfe_u32 v184, v187, 22, 10
	v_bfe_u32 v185, v187, 21, 1
	v_lshl_add_u32 v184, v184, 2, v100
	v_mad_u32_u24 v185, v185, s11, 1
	ds_add_u32 v184, v185

.Lidx_lddone1:
	s_cmp_gt_i32 s17, s13
	s_cbranch_scc1 .Lidx_exit_prev0
	s_cmp_gt_i32 s14, s19
	s_cbranch_scc1 .Lidx_edge1
	s_waitcnt vmcnt(7)
	v_mfma_f32_32x32x16_bf16 v[4:19], v[44:47], v[96:99], 0
	v_max_i32_e32 v177, 0, v20
	v_max_i32_e32 v176, 0, v28
	v_max_i32_e32 v179, 0, v21
	v_pk_fma_f32 v[176:177], v[134:135], v[176:177], 0 op_sel_hi:[1,1,0]
	v_max_i32_e32 v178, 0, v29
	v_max_i32_e32 v181, 0, v22
	v_max_i32_e32 v180, 0, v30
	v_pk_fma_f32 v[176:177], v[36:37], v[178:179], v[176:177]
	v_lshl_add_u32 v189, s14, 7, v175
	v_pk_fma_f32 v[176:177], v[136:137], v[180:181], v[176:177]
	s_waitcnt vmcnt(6)
	v_mfma_f32_32x32x16_bf16 v[4:19], v[48:51], v[92:95], v[4:19]
	v_max_i32_e32 v179, 0, v23
	v_max_i32_e32 v178, 0, v31
	v_pk_fma_f32 v[176:177], v[38:39], v[178:179], v[176:177]
	v_max_i32_e32 v179, 0, v24
	v_max_i32_e32 v178, 0, v32
	v_pk_fma_f32 v[176:177], v[138:139], v[178:179], v[176:177]
	v_max_i32_e32 v179, 0, v25
	v_max_i32_e32 v178, 0, v33
	v_pk_fma_f32 v[176:177], v[40:41], v[178:179], v[176:177]
	v_max_i32_e32 v179, 0, v26
	s_waitcnt vmcnt(5)
	v_mfma_f32_32x32x16_bf16 v[4:19], v[52:55], v[88:91], v[4:19]
	v_max_i32_e32 v178, 0, v34
	v_pk_fma_f32 v[176:177], v[140:141], v[178:179], v[176:177]
	v_max_i32_e32 v179, 0, v27
	v_max_i32_e32 v178, 0, v35
	v_pk_fma_f32 v[176:177], v[42:43], v[178:179], v[176:177]
	s_nop 0
	v_ashrrev_i32_e32 v182, 31, v177
	v_ashrrev_i32_e32 v183, 31, v176
	v_bitop3_b32 v186, v177, v182, s18 bitop3:0x1e
	v_bitop3_b32 v187, v176, v183, s18 bitop3:0x1e
	s_waitcnt vmcnt(4)
	v_mfma_f32_32x32x16_bf16 v[4:19], v[56:59], v[84:87], v[4:19]
	ds_write2st64_b32 v189, v186, v187 offset1:128
	v_bfe_u32 v190, v186, 22, 10
	v_bfe_u32 v191, v186, 21, 1
	v_lshl_add_u32 v190, v190, 2, v165
	v_mad_u32_u24 v191, v191, s11, 1
	ds_add_u32 v190, v191
	v_bfe_u32 v184, v187, 22, 10
	v_bfe_u32 v185, v187, 21, 1
	v_lshl_add_u32 v184, v184, 2, v100
	v_mad_u32_u24 v185, v185, s11, 1
	ds_add_u32 v184, v185

.Lidx_edge0:
	s_waitcnt vmcnt(7)
	v_mfma_f32_32x32x16_bf16 v[20:35], v[44:47], v[80:83], 0
	s_waitcnt vmcnt(6)
	v_mfma_f32_32x32x16_bf16 v[20:35], v[48:51], v[76:79], v[20:35]
	s_waitcnt vmcnt(5)
	v_mfma_f32_32x32x16_bf16 v[20:35], v[52:55], v[72:75], v[20:35]
	s_waitcnt vmcnt(4)
	v_mfma_f32_32x32x16_bf16 v[20:35], v[56:59], v[68:71], v[20:35]
	v_max_i32_e32 v177, 0, v4
	v_max_i32_e32 v176, 0, v12
	v_max_i32_e32 v179, 0, v5
	v_pk_fma_f32 v[176:177], v[134:135], v[176:177], 0 op_sel_hi:[1,1,0]
	v_max_i32_e32 v178, 0, v13
	v_max_i32_e32 v181, 0, v6
	v_max_i32_e32 v180, 0, v14
	v_pk_fma_f32 v[176:177], v[36:37], v[178:179], v[176:177]
	v_lshl_or_b32 v188, s14, 5, v164
	v_pk_fma_f32 v[176:177], v[136:137], v[180:181], v[176:177]
	v_max_i32_e32 v179, 0, v7
	v_max_i32_e32 v178, 0, v15
	v_pk_fma_f32 v[176:177], v[38:39], v[178:179], v[176:177]
	v_max_i32_e32 v179, 0, v8
	v_max_i32_e32 v178, 0, v16
	v_pk_fma_f32 v[176:177], v[138:139], v[178:179], v[176:177]
	v_max_i32_e32 v179, 0, v9
	v_max_i32_e32 v178, 0, v17
	v_pk_fma_f32 v[176:177], v[40:41], v[178:179], v[176:177]
	v_max_i32_e32 v179, 0, v10
	v_max_i32_e32 v178, 0, v18
	v_pk_fma_f32 v[176:177], v[140:141], v[178:179], v[176:177]
	v_max_i32_e32 v179, 0, v11
	v_max_i32_e32 v178, 0, v19
	v_pk_fma_f32 v[176:177], v[42:43], v[178:179], v[176:177]
	s_nop 0
	v_and_b32_e32 v183, 0x7fffffff, v177
	v_and_b32_e32 v182, 0x7fffffff, v176
	v_xor_b32_e32 v185, -1, v177
	v_pk_add_f32 v[182:183], v[182:183], 0 neg_lo:[1,1] neg_hi:[1,1]
	v_cmp_gt_i32_e32 vcc, 0, v177
	v_xor_b32_e32 v184, -1, v176
	s_nop 0
	v_cndmask_b32_e32 v186, v183, v185, vcc
	v_cmp_gt_i32_e32 vcc, 0, v176
	s_nop 1
	v_cndmask_b32_e32 v187, v182, v184, vcc
	v_cmp_le_i32_e32 vcc, v188, v132
	s_nop 1
	v_cndmask_b32_e32 v187, 0, v187, vcc
	v_cmp_le_i32_e32 vcc, v188, v1
	v_lshl_add_u32 v189, s14, 7, v175
	s_nop 0
	v_cndmask_b32_e32 v186, 0, v186, vcc
	ds_write2st64_b32 v189, v186, v187 offset1:128
	v_lshrrev_b32_e32 v190, 20, v186
	v_cmp_eq_u32_e32 vcc, 0, v186
	v_lshrrev_b32_e32 v191, 17, v186
	v_and_b32_e32 v190, 0xffc, v190
	v_and_b32_e32 v191, 16, v191
	v_add_u32_e32 v190, v165, v190
	v_lshlrev_b32_e64 v191, v191, 1
	v_cndmask_b32_e32 v190, v190, v166, vcc
	v_cndmask_b32_e64 v191, v191, 0, vcc
	ds_add_u32 v190, v191
	v_lshrrev_b32_e32 v190, 20, v187
	v_cmp_eq_u32_e32 vcc, 0, v187
	v_lshrrev_b32_e32 v191, 17, v187
	v_and_b32_e32 v190, 0xffc, v190
	v_and_b32_e32 v191, 16, v191
	v_add3_u32 v190, v165, v190, s73
	v_lshlrev_b32_e64 v191, v191, 1
	v_cndmask_b32_e32 v190, v190, v166, vcc
	v_cndmask_b32_e64 v191, v191, 0, vcc
	ds_add_u32 v190, v191
	s_branch .Lidx_postdone0
.Lidx_nopost0:
	s_waitcnt vmcnt(7)
	v_mfma_f32_32x32x16_bf16 v[20:35], v[44:47], v[80:83], 0
	s_waitcnt vmcnt(6)
	v_mfma_f32_32x32x16_bf16 v[20:35], v[48:51], v[76:79], v[20:35]
	s_waitcnt vmcnt(5)
	v_mfma_f32_32x32x16_bf16 v[20:35], v[52:55], v[72:75], v[20:35]
	s_waitcnt vmcnt(4)
	v_mfma_f32_32x32x16_bf16 v[20:35], v[56:59], v[68:71], v[20:35]
	s_waitcnt lgkmcnt(0)
	s_branch .Lidx_join0
.Lidx_edge1:
	s_waitcnt vmcnt(7)
	v_mfma_f32_32x32x16_bf16 v[4:19], v[44:47], v[96:99], 0
	s_waitcnt vmcnt(6)
	v_mfma_f32_32x32x16_bf16 v[4:19], v[48:51], v[92:95], v[4:19]
	s_waitcnt vmcnt(5)
	v_mfma_f32_32x32x16_bf16 v[4:19], v[52:55], v[88:91], v[4:19]
	s_waitcnt vmcnt(4)
	v_mfma_f32_32x32x16_bf16 v[4:19], v[56:59], v[84:87], v[4:19]
	v_max_i32_e32 v177, 0, v20
	v_max_i32_e32 v176, 0, v28
	v_max_i32_e32 v179, 0, v21
	v_pk_fma_f32 v[176:177], v[134:135], v[176:177], 0 op_sel_hi:[1,1,0]
	v_max_i32_e32 v178, 0, v29
	v_max_i32_e32 v181, 0, v22
	v_max_i32_e32 v180, 0, v30
	v_pk_fma_f32 v[176:177], v[36:37], v[178:179], v[176:177]
	v_lshl_or_b32 v188, s14, 5, v164
	v_pk_fma_f32 v[176:177], v[136:137], v[180:181], v[176:177]
	v_max_i32_e32 v179, 0, v23
	v_max_i32_e32 v178, 0, v31
	v_pk_fma_f32 v[176:177], v[38:39], v[178:179], v[176:177]
	v_max_i32_e32 v179, 0, v24
	v_max_i32_e32 v178, 0, v32
	v_pk_fma_f32 v[176:177], v[138:139], v[178:179], v[176:177]
	v_max_i32_e32 v179, 0, v25
	v_max_i32_e32 v178, 0, v33
	v_pk_fma_f32 v[176:177], v[40:41], v[178:179], v[176:177]
	v_max_i32_e32 v179, 0, v26
	v_max_i32_e32 v178, 0, v34
	v_pk_fma_f32 v[176:177], v[140:141], v[178:179], v[176:177]
	v_max_i32_e32 v179, 0, v27
	v_max_i32_e32 v178, 0, v35
	v_pk_fma_f32 v[176:177], v[42:43], v[178:179], v[176:177]
	s_nop 0
	v_and_b32_e32 v183, 0x7fffffff, v177
	v_and_b32_e32 v182, 0x7fffffff, v176
	v_xor_b32_e32 v185, -1, v177
	v_pk_add_f32 v[182:183], v[182:183], 0 neg_lo:[1,1] neg_hi:[1,1]
	v_cmp_gt_i32_e32 vcc, 0, v177
	v_xor_b32_e32 v184, -1, v176
	s_nop 0
	v_cndmask_b32_e32 v186, v183, v185, vcc
	v_cmp_gt_i32_e32 vcc, 0, v176
	s_nop 1
	v_cndmask_b32_e32 v187, v182, v184, vcc
	v_cmp_le_i32_e32 vcc, v188, v132
	s_nop 1
	v_cndmask_b32_e32 v187, 0, v187, vcc
	v_cmp_le_i32_e32 vcc, v188, v1
	v_lshl_add_u32 v189, s14, 7, v175
	s_nop 0
	v_cndmask_b32_e32 v186, 0, v186, vcc
	ds_write2st64_b32 v189, v186, v187 offset1:128
	v_lshrrev_b32_e32 v190, 20, v186
	v_cmp_eq_u32_e32 vcc, 0, v186
	v_lshrrev_b32_e32 v191, 17, v186
	v_and_b32_e32 v190, 0xffc, v190
	v_and_b32_e32 v191, 16, v191
	v_add_u32_e32 v190, v165, v190
	v_lshlrev_b32_e64 v191, v191, 1
	v_cndmask_b32_e32 v190, v190, v166, vcc
	v_cndmask_b32_e64 v191, v191, 0, vcc
	ds_add_u32 v190, v191
	v_lshrrev_b32_e32 v190, 20, v187
	v_cmp_eq_u32_e32 vcc, 0, v187
	v_lshrrev_b32_e32 v191, 17, v187
	v_and_b32_e32 v190, 0xffc, v190
	v_and_b32_e32 v191, 16, v191
	v_add3_u32 v190, v165, v190, s73
	v_lshlrev_b32_e64 v191, v191, 1
	v_cndmask_b32_e32 v190, v190, v166, vcc
	v_cndmask_b32_e64 v191, v191, 0, vcc
	ds_add_u32 v190, v191
	s_branch .Lidx_postdone1

.LBB0_975:
	s_or_b64 exec, exec, s[4:5]
	v_mov_b32_e32 v15, v202
	s_add_u32 s62, s28, 0x14000000
	s_waitcnt lgkmcnt(0)
	s_barrier
	s_nop 0
	s_nop 0
	s_nop 0
	s_nop 0
	s_nop 0
	s_nop 0
	s_nop 0
	s_nop 0
	s_nop 0
	s_nop 0
	s_nop 0
	s_nop 0
	s_nop 0
	s_nop 0
	s_nop 0
	s_nop 0
	s_nop 0
	s_nop 0
	s_nop 0
	s_nop 0
	s_nop 0
	s_nop 0
	s_nop 0
	s_nop 0
	s_nop 0
	s_nop 0
	s_nop 0
	s_nop 0
	s_nop 0
	s_nop 0
	s_nop 0
	s_nop 0
	s_nop 0
	s_nop 0
	s_nop 0
	s_nop 0
	s_nop 0
	s_nop 0
	s_nop 0
	s_nop 0
	s_addc_u32 s63, s29, 0
	v_readfirstlane_b32 s4, v15
	s_ashr_i32 s4, s4, 6
	s_and_b64 s[6:7], s[46:47], exec
	s_cselect_b32 s5, 8, 1
	v_cvt_f32_ubyte0_e32 v1, s5
	v_rcp_iflag_f32_e32 v1, v1
	s_add_i32 s8, s5, -1
	s_and_b64 s[6:7], s[46:47], exec
	s_cselect_b32 s24, 3, 0
	v_mul_f32_e32 v1, 0x4f7ffffe, v1
	v_cvt_u32_f32_e32 v1, v1
	s_sub_i32 s9, 0, s5
	s_abs_i32 s7, s30
	s_lshr_b32 s6, s2, s24
	v_readfirstlane_b32 s10, v1
	s_mul_i32 s9, s9, s10
	s_mul_hi_u32 s9, s10, s9
	s_add_i32 s10, s10, s9
	s_mul_hi_u32 s9, s7, s10
	s_mul_i32 s10, s9, s5
	s_sub_i32 s7, s7, s10
	s_lshl_b32 s6, s6, 3
	s_ashr_i32 s68, s30, 31
	s_add_i32 s10, s9, 1
	s_sub_i32 s11, s7, s5
	s_cmp_ge_u32 s7, s5
	s_cselect_b32 s9, s10, s9
	s_cselect_b32 s7, s11, s7
	s_add_i32 s10, s9, 1
	s_cmp_ge_u32 s7, s5
	s_cselect_b32 s7, s10, s9
	s_xor_b32 s7, s7, s68
	s_sub_i32 s7, s7, s68
	s_lshl_b32 s25, s7, 3
	s_abs_i32 s7, s25
	v_cvt_f32_u32_e32 v1, s7
	s_add_i32 s40, s4, s6
	s_sub_i32 s6, s25, s40
	s_and_b32 s41, s8, s2
	v_rcp_iflag_f32_e32 v1, v1
	s_add_i32 s8, s6, 0x1fff
	s_sub_i32 s6, 0xffffe001, s6
	s_xor_b32 s9, s8, s25
	v_mul_f32_e32 v1, 0x4f7ffffe, v1
	v_cvt_u32_f32_e32 v1, v1
	s_max_i32 s6, s8, s6
	s_sub_i32 s8, 0, s7
	s_ashr_i32 s9, s9, 31
	v_readfirstlane_b32 s10, v1
	s_mul_i32 s8, s8, s10
	s_mul_hi_u32 s8, s10, s8
	s_add_i32 s10, s10, s8
	s_mul_hi_u32 s8, s6, s10
	s_mul_i32 s10, s8, s7
	s_sub_i32 s6, s6, s10
	s_add_i32 s10, s8, 1
	s_sub_i32 s11, s6, s7
	s_cmp_ge_u32 s6, s7
	s_cselect_b32 s8, s10, s8
	s_cselect_b32 s6, s11, s6
	s_add_i32 s10, s8, 1
	s_cmp_ge_u32 s6, s7
	s_cselect_b32 s6, s10, s8
	s_sub_i32 s5, s5, s41
	s_xor_b32 s6, s6, s9
	s_add_i32 s5, s5, 15
	s_sub_i32 s42, s6, s9
	s_lshr_b32 s5, s5, s24
	s_mul_i32 s43, s42, s5
	s_cmp_lt_i32 s43, 1
	s_mov_b32 s9, 0
	s_cbranch_scc1 .LBB0_980
	s_lshl_b32 s5, s4, 14
	s_lshl_b32 s4, s4, 10
	s_add_i32 s47, s4, 0
	s_lshr_b32 s8, s41, 2
	s_add_i32 s46, s5, 0
	s_add_i32 s47, s47, 0x20000
	s_and_b32 s10, s41, 3
	s_lshl_b64 s[4:5], s[8:9], 13
	s_ashr_i32 s6, s40, 31
	s_add_u32 s4, s4, s40
	s_addc_u32 s5, s5, s6
	s_lshl_b64 s[6:7], s[4:5], 9
	v_and_b32_e32 v14, 63, v15
	s_add_u32 s6, s44, s6
	s_addc_u32 s7, s45, s7
	v_lshlrev_b32_e32 v42, 3, v14
	global_load_dwordx2 v[2:3], v42, s[6:7]
	v_and_b32_e32 v17, 15, v15
	v_bfe_u32 v4, v15, 4, 2
	v_bfe_u32 v6, v15, 2, 2
	v_and_b32_e32 v1, 7, v15
	v_lshlrev_b32_e32 v34, 3, v15
	v_mov_b32_e32 v7, 0x1000
	v_lshrrev_b32_e32 v9, 3, v15
	v_or_b32_e32 v12, 16, v17
	v_lshl_or_b32 v6, v4, 2, v6
	v_bfe_u32 v5, v15, 3, 1
	v_and_b32_e32 v10, 1, v15
	v_bitop3_b32 v13, v4, v1, 4 bitop3:0x36
	v_bitop3_b32 v16, v4, v15, 7 bitop3:0x78
	v_and_or_b32 v7, v34, 24, v7
	v_xor_b32_e32 v9, v9, v15
	v_mul_u32_u24_e32 v21, 0x40004, v14
	v_lshrrev_b32_e32 v22, 3, v12
	v_lshlrev_b32_e32 v24, 4, v6
	v_lshlrev_b32_e32 v6, 7, v6
	s_cmpk_gt_i32 s40, 0xff
	s_movk_i32 s6, 0x60
	v_lshlrev_b32_e32 v12, 7, v12
	v_xor_b32_e32 v23, v13, v5
	v_xor_b32_e32 v5, v16, v5
	v_and_or_b32 v9, v9, 6, v10
	v_or_b32_e32 v60, 0x10000, v21
	v_or_b32_e32 v61, 0x30002, v21
	v_xor_b32_e32 v10, v13, v22
	v_xor_b32_e32 v13, v16, v22
	v_or_b32_e32 v16, 0x800, v6
	v_or_b32_e32 v6, v6, v7
	s_cselect_b64 vcc, -1, 0
	v_lshlrev_b32_e32 v11, 6, v15
	s_waitcnt vmcnt(2)
	v_lshlrev_b32_e32 v52, 4, v9
	v_add_u32_e32 v9, s47, v42
	v_lshl_or_b32 v37, v10, 4, v12
	v_bitop3_b32 v10, v24, v16, s6 bitop3:0xce
	v_bitop3_b32 v39, v24, v6, s6 bitop3:0xce
	s_mul_hi_u32 s6, s4, 0x1200
	s_mulk_i32 s5, 0x1200
	s_mulk_i32 s4, 0x1200
	s_add_i32 s6, s6, s5
	v_mov_b32_e32 v43, 0
	s_add_u32 s4, s38, s4
	v_mov_b32_e32 v8, 0x60
	v_lshlrev_b32_e32 v19, 7, v17
	s_addc_u32 s5, s39, s6
	v_lshl_or_b32 v35, v23, 4, v19
	v_lshl_or_b32 v36, v5, 4, v19
	v_and_b32_e32 v5, 0x60, v24
	v_bitop3_b32 v19, v24, 64, v8 bitop3:0x6c
	v_bitop3_b32 v8, v24, 32, v8 bitop3:0x6c
	v_bfe_u32 v18, v15, 3, 3
	v_lshl_or_b32 v38, v13, 4, v12
	v_or_b32_e32 v12, v19, v16
	v_or_b32_e32 v13, v8, v16
	v_or_b32_e32 v41, v8, v6
	v_or_b32_e32 v8, v5, v16
	s_waitcnt vmcnt(1)
	v_or_b32_e32 v56, v6, v5
	v_lshlrev_b32_e32 v16, 3, v4
	v_and_b32_e32 v4, 48, v15
	v_mov_b32_e32 v5, v43
	v_lshlrev_b32_e32 v63, 6, v18
	v_bitop3_b32 v20, v18, v15, 7 bitop3:0x78
	v_or_b32_e32 v40, v19, v6
	v_add_u32_e32 v57, v10, v7
	v_add_u32_e32 v58, v12, v7
	v_add_u32_e32 v59, v13, v7
	v_add_u32_e32 v90, v8, v7
	v_add_u32_e32 v18, s47, v63
	v_mov_b32_e32 v19, v43
	v_lshlrev_b32_e32 v44, 4, v20
	v_mov_b32_e32 v45, v43
	s_mov_b32 m0, s46
	v_mov_b32_e32 v53, v43
	v_mov_b32_e32 v64, 9
	v_xor_b32_e32 v50, 16, v44
	v_mov_b32_e32 v51, v43
	v_xor_b32_e32 v48, 32, v44
	s_waitcnt vmcnt(0)
	v_cndmask_b32_e32 v2, v60, v2, vcc
	v_cndmask_b32_e32 v3, v61, v3, vcc
	ds_write_b64 v9, v[2:3]
	v_and_b32_e32 v2, 0xc0, v11
	v_lshlrev_b32_e32 v62, 1, v2
	v_lshl_or_b32 v2, s10, 9, v62
	v_mov_b32_e32 v3, v43
	v_lshl_add_u64 v[2:3], s[4:5], 0, v[2:3]
	s_lshl_b64 s[4:5], s[8:9], 22
	s_add_u32 s6, s80, s4
	v_lshl_add_u64 v[2:3], v[2:3], 0, v[4:5]
	s_addc_u32 s7, s81, s5
	global_load_dwordx4 v[10:13], v[2:3], off
	global_load_dwordx4 v[6:9], v[2:3], off offset:64
	s_waitcnt lgkmcnt(0)
	s_add_u32 s4, s37, s4
	ds_read_b128 v[30:33], v18
	ds_read_b128 v[22:25], v18 offset:16
	ds_read_b128 v[2:5], v18 offset:32
	ds_read_b128 v[26:29], v18 offset:48
	s_addc_u32 s5, s79, s5
	s_lshl_b32 s8, s10, 7
	s_add_u32 s4, s4, s8
	s_addc_u32 s5, s5, 0
	s_waitcnt lgkmcnt(3)
	v_lshlrev_b32_e32 v18, 9, v30
	s_add_u32 s6, s6, s8
	v_and_b32_e32 v18, 0x1fffe00, v18
	s_addc_u32 s7, s7, 0
	v_lshl_add_u64 v[20:21], s[4:5], 0, v[18:19]
	s_add_i32 s48, s46, 0x1000
	v_lshl_add_u64 v[20:21], v[20:21], 0, v[44:45]
	v_lshl_add_u64 v[18:19], s[6:7], 0, v[18:19]
	global_load_lds_dwordx4 v[20:21], off
	v_lshl_add_u64 v[18:19], v[18:19], 0, v[52:53]
	s_mov_b32 m0, s48
	s_add_i32 s49, s46, 0x400
	global_load_lds_dwordx4 v[18:19], off
	v_lshlrev_b32_sdwa v18, v64, v30 dst_sel:DWORD dst_unused:UNUSED_PAD src0_sel:DWORD src1_sel:WORD_1
	v_mov_b32_e32 v19, v43
	v_lshl_add_u64 v[20:21], s[4:5], 0, v[18:19]
	v_lshl_add_u64 v[20:21], v[20:21], 0, v[50:51]
	s_mov_b32 m0, s49
	v_lshl_add_u64 v[18:19], s[6:7], 0, v[18:19]
	s_add_i32 s50, s46, 0x1400
	global_load_lds_dwordx4 v[20:21], off
	v_lshl_add_u64 v[18:19], v[18:19], 0, v[52:53]
	s_mov_b32 m0, s50
	v_mov_b32_e32 v49, v43
	global_load_lds_dwordx4 v[18:19], off
	v_lshlrev_b32_e32 v18, 9, v31
	v_and_b32_e32 v18, 0x1fffe00, v18
	v_mov_b32_e32 v19, v43
	v_lshl_add_u64 v[20:21], s[4:5], 0, v[18:19]
	s_add_i32 s51, s46, 0x800
	v_lshl_add_u64 v[20:21], v[20:21], 0, v[48:49]
	s_mov_b32 m0, s51
	v_lshl_add_u64 v[18:19], s[6:7], 0, v[18:19]
	s_add_i32 s52, s46, 0x1800
	global_load_lds_dwordx4 v[20:21], off
	v_lshl_add_u64 v[18:19], v[18:19], 0, v[52:53]
	s_mov_b32 m0, s52
	v_xor_b32_e32 v46, 48, v44
	global_load_lds_dwordx4 v[18:19], off
	v_lshlrev_b32_sdwa v18, v64, v31 dst_sel:DWORD dst_unused:UNUSED_PAD src0_sel:DWORD src1_sel:WORD_1
	v_mov_b32_e32 v19, v43
	v_lshl_add_u64 v[20:21], s[4:5], 0, v[18:19]
	v_mov_b32_e32 v47, v43
	s_add_i32 s53, s46, 0xc00
	v_lshl_add_u64 v[20:21], v[20:21], 0, v[46:47]
	s_mov_b32 m0, s53
	v_lshl_add_u64 v[18:19], s[6:7], 0, v[18:19]
	s_add_i32 s54, s46, 0x1c00
	global_load_lds_dwordx4 v[20:21], off
	v_lshl_add_u64 v[18:19], v[18:19], 0, v[52:53]
	s_mov_b32 m0, s54
	v_cmp_gt_u32_e64 s[4:5], 4, v17
	global_load_lds_dwordx4 v[18:19], off
	v_and_b32_e32 v17, 0x80, v34
	v_bfe_u32 v15, v15, 5, 1
	v_or_b32_e32 v19, 32, v17
	v_or_b32_e32 v20, 64, v17
	v_or_b32_e32 v21, 0x60, v17
	v_or_b32_e32 v30, 6, v15
	v_or_b32_e32 v82, v17, v30
	v_or_b32_e32 v84, v19, v30
	v_or_b32_e32 v86, v20, v30
	v_or_b32_e32 v88, v21, v30
	v_or_b32_e32 v30, 10, v15
	v_or_b32_e32 v18, 2, v15
	v_or_b32_e32 v98, v17, v30
	v_or_b32_e32 v100, v19, v30
	v_or_b32_e32 v102, v20, v30
	v_or_b32_e32 v104, v21, v30
	v_or_b32_e32 v30, 14, v15
	v_or_b32_e32 v66, v17, v18
	v_or_b32_e32 v68, v19, v18
	v_or_b32_e32 v70, v20, v18
	v_or_b32_e32 v72, v21, v18
	v_or_b32_e32 v18, 4, v15
	v_or_b32_e32 v106, v17, v30
	v_or_b32_e32 v108, v19, v30
	v_or_b32_e32 v110, v20, v30
	v_or_b32_e32 v112, v21, v30
	v_or_b32_e32 v30, 18, v15
	v_or_b32_e32 v81, v17, v18
	v_or_b32_e32 v83, v19, v18
	v_or_b32_e32 v85, v20, v18
	v_or_b32_e32 v87, v21, v18
	v_or_b32_e32 v18, 8, v15
	v_or_b32_e32 v114, v17, v30
	v_or_b32_e32 v116, v19, v30
	v_or_b32_e32 v118, v20, v30
	v_or_b32_e32 v120, v21, v30
	v_or_b32_e32 v30, 22, v15
	v_lshl_add_u64 v[54:55], s[44:45], 0, v[42:43]
	v_or_b32_e32 v97, v17, v18
	v_or_b32_e32 v99, v19, v18
	v_or_b32_e32 v101, v20, v18
	v_or_b32_e32 v103, v21, v18
	v_or_b32_e32 v18, 12, v15
	v_or_b32_e32 v122, v17, v30
	v_or_b32_e32 v124, v19, v30
	v_or_b32_e32 v126, v20, v30
	v_or_b32_e32 v128, v21, v30
	v_or_b32_e32 v30, 26, v15
	s_abs_i32 s45, s42
	v_or_b32_e32 v105, v17, v18
	v_or_b32_e32 v107, v19, v18
	v_or_b32_e32 v109, v20, v18
	v_or_b32_e32 v111, v21, v18
	v_or_b32_e32 v18, 16, v15
	v_or_b32_e32 v130, v17, v30
	v_or_b32_e32 v132, v19, v30
	v_or_b32_e32 v134, v20, v30
	v_or_b32_e32 v136, v21, v30
	v_cvt_f32_u32_e32 v30, s45
	v_or_b32_e32 v113, v17, v18
	v_or_b32_e32 v115, v19, v18
	v_or_b32_e32 v117, v20, v18
	v_or_b32_e32 v119, v21, v18
	v_or_b32_e32 v18, 20, v15
	v_or_b32_e32 v121, v17, v18
	v_or_b32_e32 v123, v19, v18
	v_or_b32_e32 v125, v20, v18
	v_or_b32_e32 v127, v21, v18
	v_or_b32_e32 v18, 24, v15
	v_or_b32_e32 v65, v17, v15
	v_or_b32_e32 v67, v19, v15
	v_or_b32_e32 v69, v20, v15
	v_or_b32_e32 v71, v21, v15
	v_or_b32_e32 v129, v17, v18
	v_or_b32_e32 v131, v19, v18
	v_or_b32_e32 v133, v20, v18
	v_or_b32_e32 v135, v21, v18
	v_or_b32_e32 v18, 28, v15
	v_or_b32_e32 v15, 30, v15
	v_or_b32_e32 v137, v17, v18
	v_or_b32_e32 v138, v17, v15
	v_rcp_iflag_f32_e32 v17, v30
	s_sub_i32 s8, 0, s45
	s_add_i32 s44, s46, 0x2000
	v_lshlrev_b32_e32 v1, 2, v14
	v_mul_f32_e32 v17, 0x4f7ffffe, v17
	v_cvt_u32_f32_e32 v17, v17
	s_waitcnt vmcnt(0)
	v_cndmask_b32_e64 v9, 0, v9, s[4:5]
	v_cndmask_b32_e64 v8, 0, v8, s[4:5]
	v_cndmask_b32_e64 v7, 0, v7, s[4:5]
	v_readfirstlane_b32 s10, v17
	s_mul_i32 s8, s8, s10
	s_mul_hi_u32 s8, s10, s8
	v_cndmask_b32_e64 v6, 0, v6, s[4:5]
	v_cndmask_b32_e64 v13, 0, v13, s[4:5]
	v_cndmask_b32_e64 v12, 0, v12, s[4:5]
	v_cndmask_b32_e64 v11, 0, v11, s[4:5]
	v_cndmask_b32_e64 v10, 0, v10, s[4:5]
	v_cmp_gt_u32_e64 s[6:7], 16, v14
	v_add_u32_e32 v73, s46, v56
	v_add_u32_e32 v74, s46, v90
	v_add_u32_e32 v75, s46, v41
	v_add_u32_e32 v76, s46, v59
	v_add_u32_e32 v77, s46, v40
	v_add_u32_e32 v78, s46, v58
	v_add_u32_e32 v79, s46, v39
	v_add_u32_e32 v80, s46, v57
	v_add_u32_e32 v89, s44, v56
	v_add_u32_e32 v90, s44, v90
	v_add_u32_e32 v91, s44, v41
	v_add_u32_e32 v92, s44, v59
	v_add_u32_e32 v93, s44, v40
	v_add_u32_e32 v94, s44, v58
	v_add_u32_e32 v95, s44, v39
	v_add_u32_e32 v96, s44, v57
	v_or_b32_e32 v139, v19, v18
	v_or_b32_e32 v140, v19, v15
	v_or_b32_e32 v141, v20, v18
	v_or_b32_e32 v142, v20, v15
	v_or_b32_e32 v143, v21, v18
	v_or_b32_e32 v144, v21, v15
	s_ashr_i32 s55, s42, 31
	s_add_i32 s56, s10, s8
	s_sub_i32 s57, 0, s42
	v_lshlrev_b32_e32 v56, 1, v16
	s_add_i32 s58, s46, 0x3000
	s_add_i32 s59, s46, 0x2400
	s_add_i32 s60, s46, 0x3400
	s_add_i32 s61, s46, 0x2800
	s_add_i32 s64, s46, 0x3800
	s_add_i32 s65, s46, 0x2c00
	s_add_i32 s66, s46, 0x3c00
	v_add_u32_e32 v145, s46, v36
	v_add_u32_e32 v149, s46, v35
	v_add_u32_e32 v151, s46, v38
	v_add_u32_e32 v153, s46, v37
	v_lshlrev_b32_e32 v58, 1, v14
	s_movk_i32 s67, 0x7fff
	s_mov_b32 s69, 0
	s_mov_b32 s70, 0
	s_branch .LBB0_978
